# LayerNorm row loops: 8-row waves pause (s_sleep 10) each row so the 9-row waves that end the phase get the memory system first
# baseline (speedup 1.0000x reference)
.LBB0_1221:
	s_cmp_eq_u32 s11, 9
	s_cbranch_scc1 .Lmy_lny_a
	s_sleep 10

.LBB0_1437:
	s_cmp_eq_u32 s23, 9
	s_cbranch_scc1 .Lmy_lny_c
	s_sleep 10

.LBB0_1470:
	s_cmp_eq_u32 s13, 9
	s_cbranch_scc1 .Lmy_lny_b
	s_sleep 10
